# speedup vs baseline: 1.0131x; 1.0000x over previous
; #define R2_LOAD_K(nn) do { const bf16* kdt_ = KDT + ((size_t)bh * 64 + (nn)) * 32768; \
;     _Pragma("unroll") for (int q = 0; q < 4; ++q) { kfr[2 * q] = *(const bf16x8*)(kdt_ + ((2 * wave) * 16 + r16) * 128 + q * 32 + g4 * 8); kfr[2 * q + 1] = *(const bf16x8*)(kdt_ + ((2 * wave + 1) * 16 + r16) * 128 + q * 32 + g4 * 8); } } while (0)
; __global__ void __launch_bounds__(512, 2) fwd_megakernel(Params kp_) {
;     ...
;                             const float lg = log1pf(-exp2f(-5.f - (float)h)), gam = __expf(lg * 128.f);
;                             __syncthreads();
;                             for (int i = tid; i < R2_NCT * 16 * 264; i += 512) ST0[i] = 0;
;                             f32x4 Sacc[R2_NCT][2];
; #pragma unroll
;                             for (int a = 0; a < R2_NCT; ++a) { Sacc[a][0] = (f32x4){0.f, 0.f, 0.f, 0.f}; Sacc[a][1] = (f32x4){0.f, 0.f, 0.f, 0.f}; }
;                             __syncthreads();
;                             bf16x8 afr[12], kfr[8]; u32x4 vreg[R2_NCT / 2];
;     ...
;                             R2_LOAD_A((size_t)b * SEQ); R2_LOAD_K(0);
.LBB0_557:
	s_or_b64 exec, exec, s[2:3]
	v_add_f32_e32 v2, -1.0, v1
	v_sub_f32_e32 v3, v2, v1
	v_add_f32_e32 v3, 1.0, v3
	v_sub_f32_e64 v2, -v0, v2
	v_add_f32_e32 v4, v2, v3
	v_cvt_f64_f32_e32 v[2:3], v1
	v_frexp_exp_i32_f64_e32 v2, v[2:3]
	v_subbrev_co_u32_e64 v2, s[0:1], 0, v2, s[0:1]
	v_sub_u32_e32 v3, 0, v2
	v_ldexp_f32 v1, v1, v3
	v_ldexp_f32 v3, v4, v3
	v_add_f32_e32 v4, -1.0, v1
	v_add_f32_e32 v7, 1.0, v1
	v_add_f32_e32 v5, 1.0, v4
	v_add_f32_e32 v8, -1.0, v7
	v_sub_f32_e32 v5, v1, v5
	v_sub_f32_e32 v1, v1, v8
	v_add_f32_e32 v1, v3, v1
	v_add_f32_e32 v5, v3, v5
	v_add_f32_e32 v3, v7, v1
	v_rcp_f32_e32 v8, v3
	v_add_f32_e32 v6, v4, v5
	v_sub_f32_e32 v4, v6, v4
	v_sub_f32_e32 v4, v5, v4
	v_sub_f32_e32 v5, v3, v7
	v_sub_f32_e32 v1, v1, v5
	v_mul_f32_e32 v5, v6, v8
	v_mul_f32_e32 v7, v3, v5
	v_fma_f32 v9, v5, v3, -v7
	v_fmac_f32_e32 v9, v5, v1
	v_add_f32_e32 v10, v7, v9
	v_sub_f32_e32 v11, v6, v10
	v_sub_f32_e32 v6, v6, v11
	v_sub_f32_e32 v7, v10, v7
	v_sub_f32_e32 v6, v6, v10
	v_add_f32_e32 v4, v4, v6
	v_sub_f32_e32 v6, v7, v9
	v_add_f32_e32 v4, v6, v4
	v_add_f32_e32 v6, v11, v4
	v_mul_f32_e32 v7, v8, v6
	v_mul_f32_e32 v9, v3, v7
	v_fma_f32 v3, v7, v3, -v9
	v_fmac_f32_e32 v3, v7, v1
	v_sub_f32_e32 v1, v11, v6
	v_add_f32_e32 v1, v4, v1
	v_add_f32_e32 v4, v9, v3
	v_sub_f32_e32 v10, v6, v4
	v_sub_f32_e32 v6, v6, v10
	v_sub_f32_e32 v9, v4, v9
	v_sub_f32_e32 v4, v6, v4
	v_add_f32_e32 v1, v1, v4
	v_sub_f32_e32 v3, v9, v3
	v_cvt_f32_i32_e32 v2, v2
	v_add_f32_e32 v1, v3, v1
	v_add_f32_e32 v3, v5, v7
	v_add_f32_e32 v1, v10, v1
	v_sub_f32_e32 v4, v3, v5
	v_mul_f32_e32 v1, v8, v1
	v_sub_f32_e32 v4, v7, v4
	v_add_f32_e32 v1, v4, v1
	v_mul_f32_e32 v7, 0x3f317218, v2
	s_mov_b32 s0, 0x3f317218
	v_add_f32_e32 v4, v3, v1
	v_fma_f32 v8, v2, s0, -v7
	v_mul_f32_e32 v5, v4, v4
	v_mov_b32_e32 v6, 0x3ecc95a3
	v_fmac_f32_e32 v8, 0xb102e308, v2
	v_sub_f32_e32 v2, v4, v3
	v_fmamk_f32 v6, v5, 0x3e9b6dac, v6
	v_sub_f32_e32 v1, v1, v2
	v_add_f32_e32 v2, v7, v8
	v_fmaak_f32 v6, v5, v6, 0x3f2aaada
	v_sub_f32_e32 v3, v2, v7
	v_ldexp_f32 v7, v4, 1
	v_mul_f32_e32 v4, v4, v5
	v_mul_f32_e32 v4, v4, v6
	v_add_f32_e32 v5, v7, v4
	v_sub_f32_e32 v6, v5, v7
	v_ldexp_f32 v1, v1, 1
	v_sub_f32_e32 v4, v4, v6
	v_add_f32_e32 v1, v1, v4
	v_add_f32_e32 v4, v5, v1
	v_sub_f32_e32 v5, v4, v5
	v_sub_f32_e32 v1, v1, v5
	v_add_f32_e32 v5, v2, v4
	v_sub_f32_e32 v6, v5, v2
	v_sub_f32_e32 v7, v5, v6
	v_sub_f32_e32 v3, v8, v3
	v_sub_f32_e32 v2, v2, v7
	v_sub_f32_e32 v4, v4, v6
	v_add_f32_e32 v2, v4, v2
	v_add_f32_e32 v4, v3, v1
	v_sub_f32_e32 v6, v4, v3
	v_sub_f32_e32 v7, v4, v6
	v_sub_f32_e32 v3, v3, v7
	v_sub_f32_e32 v1, v1, v6
	v_add_f32_e32 v2, v4, v2
	v_add_f32_e32 v1, v1, v3
	v_add_f32_e32 v3, v5, v2
	v_sub_f32_e32 v4, v3, v5
	v_sub_f32_e32 v2, v2, v4
	v_add_f32_e32 v1, v1, v2
	v_add_f32_e32 v1, v3, v1
	v_mov_b32_e32 v2, 0x7fc00000
	v_cndmask_b32_e64 v1, v2, v1, s[4:5]
	v_mov_b32_e32 v2, 0xff800000
	v_cndmask_b32_e64 v1, v2, v1, s[6:7]
	s_lshl_b32 s0, s18, 4
	v_cndmask_b32_e64 v0, v1, -v0, s[8:9]
	s_sub_i32 s1, s19, s0
	s_ashr_i32 s0, s12, 2
	v_mul_f32_e32 v0, 0x43000000, v0
	s_lshl_b32 s2, s1, 5
	s_ashr_i32 s1, s0, 31
	v_mul_f32_e32 v0, 0x3fb8aa3b, v0
	s_lshl_b64 s[6:7], s[0:1], 13
	v_exp_f32_e32 v114, v0
	v_lshl_add_u64 v[0:1], s[6:7], 0, v[172:173]
	s_waitcnt vmcnt(2)
	v_mov_b64_e32 v[44:45], s[52:53]
	v_mad_u64_u32 v[2:3], s[0:1], v0, s69, v[44:45]
	v_mov_b32_e32 v0, v3
	v_lshl_add_u64 v[46:47], s[6:7], 0, v[104:105]
	v_mad_u64_u32 v[0:1], s[0:1], v1, s69, v[0:1]
	v_mad_u64_u32 v[44:45], s[0:1], v46, s69, v[44:45]
	v_mad_i32_i24 v45, v47, s69, v45
	s_lshl_b32 s0, s13, 10
	s_mov_b32 s1, s95
	s_ashr_i32 s3, s2, 31
	v_lshl_add_u64 v[44:45], v[44:45], 0, s[0:1]
	s_lshl_b64 s[4:5], s[2:3], 1
	v_lshl_add_u64 v[44:45], v[44:45], 0, s[4:5]
	v_mov_b32_e32 v113, v197
	v_mov_b32_e32 v3, v0
	s_lshl_b32 s94, s13, 9
	v_lshl_add_u64 v[44:45], v[44:45], 0, v[112:113]
	v_lshl_add_u64 v[0:1], v[2:3], 0, s[94:95]
	v_lshlrev_b32_e32 v196, 1, v102
	v_add_co_u32_e64 v44, s[0:1], s64, v44
	v_lshl_add_u64 v[176:177], v[0:1], 0, v[174:175]
	s_nop 0
	v_addc_co_u32_e64 v45, s[0:1], 0, v45, s[0:1]
	s_ashr_i32 s13, s12, 31
	s_waitcnt lgkmcnt(0)
	s_barrier
	global_load_dwordx4 v[60:63], v[176:177], off
	global_load_dwordx4 v[12:15], v[176:177], off offset:2048
	v_lshl_add_u64 v[176:177], v[176:177], 0, v[170:171]
	global_load_dwordx4 v[40:43], v[176:177], off
	global_load_dwordx4 v[8:11], v[176:177], off offset:2048
	v_lshl_add_u64 v[176:177], v[176:177], 0, v[170:171]
	global_load_dwordx4 v[36:39], v[176:177], off
	global_load_dwordx4 v[4:7], v[176:177], off offset:2048
	v_lshl_add_u64 v[176:177], v[176:177], 0, v[170:171]
	global_load_dwordx4 v[32:35], v[176:177], off
	global_load_dwordx4 v[0:3], v[176:177], off offset:2048
	v_lshl_add_u64 v[176:177], v[176:177], 0, v[170:171]
	global_load_dwordx4 v[28:31], v[176:177], off
	v_lshl_add_u64 v[176:177], v[176:177], 0, v[170:171]
	global_load_dwordx4 v[24:27], v[176:177], off
	v_lshl_add_u64 v[176:177], v[176:177], 0, v[170:171]
	global_load_dwordx4 v[20:23], v[176:177], off
	v_lshl_add_u64 v[176:177], v[176:177], 0, v[170:171]
	global_load_dwordx4 v[16:19], v[176:177], off
	s_lshl_b64 s[0:1], s[12:13], 22
	v_lshl_add_u64 v[116:117], v[108:109], 0, s[0:1]
	v_mov_b64_e32 v[46:47], v[116:117]
	global_load_dwordx4 v[84:87], v[44:45], off
	global_load_dwordx4 v[52:55], v[46:47], off
	v_add_co_u32_e64 v44, s[0:1], s64, v46
	s_waitcnt vmcnt(14)
; #define LBAR() asm volatile("s_waitcnt lgkmcnt(0)\n\ts_barrier" ::: "memory")
; #define MFMA16(a, b, c) __builtin_amdgcn_mfma_f32_16x16x32_bf16((a), (b), (c), 0, 0, 0)
; #define R2_LOAD_K(nn) do { const bf16* kdt_ = KDT + ((size_t)bh * 64 + (nn)) * 32768; \
;     _Pragma("unroll") for (int q = 0; q < 4; ++q) { kfr[2 * q] = *(const bf16x8*)(kdt_ + ((2 * wave) * 16 + r16) * 128 + q * 32 + g4 * 8); kfr[2 * q + 1] = *(const bf16x8*)(kdt_ + ((2 * wave + 1) * 16 + r16) * 128 + q * 32 + g4 * 8); } } while (0)
; __global__ void __launch_bounds__(512, 2) fwd_megakernel(Params kp_) {
;     ...
;                             R2_LOAD_A((size_t)b * SEQ); R2_LOAD_K(0);
; #pragma unroll 1
;                             for (int n = 0; n < 64; ++n) {
;                                 const size_t row0 = (size_t)b * SEQ + n * 128;
;                                 bf16* ST = ST0 + (n & 1) * (R2_NCT * 16 * 264); bf16* STn = ST0 + ((n + 1) & 1) * (R2_NCT * 16 * 264); bf16* VT = VT0 + (n & 1) * (R2_NCT * 16 * 136);
; #pragma unroll
;                                 for (int it = 0; it < R2_NCT / 2; ++it) { const int idx_ = tid + 512 * it, i = idx_ >> 2, c8 = idx_ & 3; const u32x4 w = vreg[it];
; #pragma unroll
;                                     for (int e = 0; e < 4; ++e) { VT[(c8 * 8 + 2 * e) * 136 + i] = (bf16)(w[e] & 0xffffu); VT[(c8 * 8 + 2 * e + 1) * 136 + i] = (bf16)(w[e] >> 16); } }
;                                 LBAR();
;                                 f32x4 acc[R2_NCT];
; #pragma unroll
;                                 for (int ct = 0; ct < R2_NCT; ++ct) acc[ct] = (f32x4){0.f, 0.f, 0.f, 0.f};
;                                 {
;                                     bf16x8 bq[3][R2_NCT];
;     ...
;                                     R2_BLOAD(0, 0); R2_BLOAD(1, 1);
; #pragma unroll
;                                     for (int q = 0; q < 12; ++q) {
;                                         if (q + 2 < 12) R2_BLOAD((q + 2) % 3, q + 2);
;                                         __builtin_amdgcn_sched_barrier(0);
; #pragma unroll
;                                         for (int ct = 0; ct < R2_NCT; ++ct) acc[ct] = MFMA16(bq[q % 3][ct], afr[q], acc[ct]);
	v_lshl_add_u64 v[56:57], v[46:47], 0, s[90:91]
	v_addc_co_u32_e64 v45, s[0:1], 0, v47, s[0:1]
	global_load_dwordx4 v[76:79], v[44:45], off
	global_load_dwordx4 v[68:71], v[46:47], off offset:1024
	global_load_dwordx4 v[48:51], v[46:47], off offset:2048
	global_load_dwordx4 v[72:75], v[56:57], off offset:1024
	s_nop 0
	global_load_dwordx4 v[44:47], v[46:47], off offset:3072
	s_nop 0
	global_load_dwordx4 v[64:67], v[56:57], off offset:2048
	s_nop 0
	global_load_dwordx4 v[56:59], v[56:57], off offset:3072
	s_mov_b32 s100, 0x8000
	s_mov_b32 s101, 0
	v_lshl_add_u64 v[232:233], s[100:101], 1, v[116:117]
	s_nop 0
	v_add_co_u32_e64 v236, s[0:1], s64, v232
	v_lshl_add_u64 v[234:235], v[232:233], 0, s[90:91]
	s_nop 0
	v_addc_co_u32_e64 v237, s[0:1], 0, v233, s[0:1]
	global_load_dwordx4 v[200:203], v[232:233], off
	global_load_dwordx4 v[204:207], v[232:233], off offset:1024
	global_load_dwordx4 v[208:211], v[234:235], off offset:1024
	global_load_dwordx4 v[212:215], v[234:235], off offset:2048
	global_load_dwordx4 v[216:219], v[232:233], off offset:2048
	global_load_dwordx4 v[220:223], v[232:233], off offset:3072
	global_load_dwordx4 v[224:227], v[236:237], off
	global_load_dwordx4 v[228:231], v[234:235], off offset:3072
	s_and_b32 s1, s16, 2
	s_add_i32 s1, s1, s18
	s_and_b32 s1, s1, 3
	s_lshl_b32 s1, s1, 10
	s_add_u32 s4, s4, s1
	s_addc_u32 s5, s5, 0
	v_lshl_add_u64 v[80:81], v[100:101], 0, s[6:7]
	v_mov_b64_e32 v[82:83], s[4:5]
	v_mad_u64_u32 v[82:83], s[4:5], v80, s69, v[82:83]
	v_mov_b32_e32 v80, v83
	v_mad_u64_u32 v[80:81], s[4:5], v81, s69, v[80:81]
	v_mov_b32_e32 v83, v80
	v_mov_b32_e32 v80, 0
	s_mov_b32 s0, 0
	v_lshl_add_u64 v[118:119], v[106:107], 0, s[94:95]
	v_lshl_add_u64 v[180:181], v[182:183], 0, s[94:95]
	v_mov_b32_e32 v120, v114
	v_mov_b32_e32 v121, v114
	v_lshl_add_u64 v[122:123], v[110:111], 0, v[82:83]
	s_mov_b32 s8, 0x8000
	s_lshl_b32 s94, s94, 1
	v_mov_b32_e32 v81, v80
	v_mov_b32_e32 v82, v80
	v_mov_b32_e32 v83, v80
	v_mov_b32_e32 v88, v80
	v_mov_b32_e32 v89, v80
	v_mov_b32_e32 v90, v80
	v_mov_b32_e32 v91, v80
	v_mov_b32_e32 v92, v80
	v_mov_b32_e32 v93, v80
	v_mov_b32_e32 v94, v80
	v_mov_b32_e32 v95, v80
	v_mov_b32_e32 v96, v80
	v_mov_b32_e32 v97, v80
	v_mov_b32_e32 v98, v80
	v_mov_b32_e32 v99, v80
.LBB0_558:
	s_and_b32 s1, s0, 1
	s_mul_i32 s4, s1, 0x2200
	s_add_i32 s11, s4, 0
	s_lshl_b32 s1, s1, 13
	v_lshlrev_b32_e32 v115, 1, v104
	s_add_i32 s1, s11, s1
	v_add3_u32 v131, s11, v115, v103
	v_add3_u32 v115, s11, v103, v115
	s_waitcnt vmcnt(8)
	ds_write_b16 v131, v84 offset:33792
	ds_write_b16_d16_hi v115, v84 offset:34064
	ds_write_b16 v131, v85 offset:34336
	ds_write_b16_d16_hi v115, v85 offset:34608
	ds_write_b16 v131, v86 offset:34880
	ds_write_b16_d16_hi v115, v86 offset:35152
	ds_write_b16 v131, v87 offset:35424
	ds_write_b16_d16_hi v115, v87 offset:35696
	v_add_u32_e32 v115, s1, v196
	s_waitcnt lgkmcnt(0)
	s_barrier
	v_add_u32_e32 v131, v115, v124
	ds_read_b128 v[84:87], v131
	ds_read_b128 v[132:135], v131 offset:8448
	v_add3_u32 v131, s1, v124, v196
	v_add_u32_e32 v115, v115, v125
	ds_read_b128 v[136:139], v131 offset:64
	ds_read_b128 v[140:143], v131 offset:128
	ds_read_b128 v[144:147], v115 offset:64
	ds_read_b128 v[148:151], v115 offset:128
	s_add_i32 s9, s0, 1
	s_and_b32 s10, 1, s9
	s_add_u32 s4, s6, 0x80
	s_addc_u32 s5, s7, 0
	s_cmp_eq_u32 s0, 63
	s_cselect_b32 s0, s6, s4
	s_cselect_b32 s6, 0x1f8000, s8
	s_cselect_b32 s1, s7, s5
	s_add_i32 s100, s6, 0x8000
	s_min_u32 s100, s100, 0x1f8000
	s_cmp_eq_u32 s10, 1
	s_waitcnt lgkmcnt(5)
	v_mfma_f32_16x16x32_bf16 v[84:87], v[84:87], v[60:63], 0
	s_waitcnt lgkmcnt(4)
	v_mfma_f32_16x16x32_bf16 v[60:63], v[132:135], v[60:63], 0
	ds_read_b128 v[132:135], v131 offset:192
	ds_read_b128 v[152:155], v115 offset:192
	s_waitcnt lgkmcnt(5)
	v_mfma_f32_16x16x32_bf16 v[84:87], v[136:139], v[40:43], v[84:87]
	s_waitcnt lgkmcnt(3)
	v_mfma_f32_16x16x32_bf16 v[40:43], v[144:147], v[40:43], v[60:63]
	s_nop 2
	ds_read_b128 v[60:63], v131 offset:256
	ds_read_b128 v[136:139], v115 offset:256
	v_mfma_f32_16x16x32_bf16 v[84:87], v[140:143], v[36:39], v[84:87]
	s_waitcnt lgkmcnt(4)
	v_mfma_f32_16x16x32_bf16 v[36:39], v[148:151], v[36:39], v[40:43]
	s_nop 2
	ds_read_b128 v[40:43], v131 offset:320
	ds_read_b128 v[140:143], v115 offset:320
	s_waitcnt lgkmcnt(5)
	v_mfma_f32_16x16x32_bf16 v[84:87], v[132:135], v[32:35], v[84:87]
	s_waitcnt lgkmcnt(4)
	v_mfma_f32_16x16x32_bf16 v[32:35], v[152:155], v[32:35], v[36:39]
	s_nop 2
	ds_read_b128 v[36:39], v131 offset:384
	ds_read_b128 v[132:135], v115 offset:384
	s_waitcnt lgkmcnt(5)
	v_mfma_f32_16x16x32_bf16 v[60:63], v[60:63], v[28:31], v[84:87]
	s_waitcnt lgkmcnt(4)
	v_mfma_f32_16x16x32_bf16 v[28:31], v[136:139], v[28:31], v[32:35]
	s_nop 2
	ds_read_b128 v[32:35], v131 offset:448
	ds_read_b128 v[84:87], v115 offset:448
	s_waitcnt lgkmcnt(5)
	v_mfma_f32_16x16x32_bf16 v[40:43], v[40:43], v[24:27], v[60:63]
	s_waitcnt lgkmcnt(4)
	v_mfma_f32_16x16x32_bf16 v[24:27], v[140:143], v[24:27], v[28:31]
	v_add3_u32 v115, s11, v126, v196
	v_add_u32_e32 v131, s11, v196
	v_add_u32_e32 v136, v131, v127
	ds_read_b128 v[28:31], v115 offset:33792
	ds_read_b128 v[60:63], v136 offset:33792
	s_waitcnt lgkmcnt(5)
	v_mfma_f32_16x16x32_bf16 v[36:39], v[36:39], v[20:23], v[40:43]
	s_waitcnt lgkmcnt(4)
	v_mfma_f32_16x16x32_bf16 v[20:23], v[132:135], v[20:23], v[24:27]
	s_nop 2
	ds_read_b128 v[24:27], v115 offset:33856
	ds_read_b128 v[40:43], v136 offset:33856
	s_waitcnt lgkmcnt(5)
	v_mfma_f32_16x16x32_bf16 v[32:35], v[32:35], v[16:19], v[36:39]
	s_waitcnt lgkmcnt(4)
	v_mfma_f32_16x16x32_bf16 v[16:19], v[84:87], v[16:19], v[20:23]
	s_nop 2
	ds_read_b128 v[20:23], v115 offset:33920
	ds_read_b128 v[36:39], v136 offset:33920
	s_waitcnt lgkmcnt(5)
; __device__ __forceinline__ unsigned pk2(float lo, float hi) { const f32x2_t v = {lo, hi}; const bf16x2_t b = __builtin_convertvector(v, bf16x2_t); return __builtin_bit_cast(unsigned, b); }
; #define MFMA16(a, b, c) __builtin_amdgcn_mfma_f32_16x16x32_bf16((a), (b), (c), 0, 0, 0)
; __global__ void __launch_bounds__(512, 2) fwd_megakernel(Params kp_) {
;     ...
;                                         for (int ct = 0; ct < R2_NCT; ++ct) acc[ct] = MFMA16(bq[q % 3][ct], afr[q], acc[ct]);
;                                         __builtin_amdgcn_sched_barrier(0);
;                                     }
;     ...
;                                 }
;                                 { const size_t rown = (n < 63) ? row0 + 128 : row0; R2_LOAD_A(rown); }
; #pragma unroll
;                                 for (int ct = 0; ct < R2_NCT; ++ct) { bf16* op = (rep_ + 1 < REP_R2) ? (dmy + (wave * 16 + r16) * 64 + ct * 16 + g4 * 4) : (proj + (row0 + wave * 16 + r16) * RETP + 2048 + h * 512 + e0 + ct * 16 + g4 * 4);
;                                     u32x2 w; w.x = pk2(acc[ct][0], acc[ct][1]); w.y = pk2(acc[ct][2], acc[ct][3]); *(u32x2*)op = w; }
; #pragma unroll
;                                 for (int a = 0; a < R2_NCT; ++a) { Sacc[a][0] = Sacc[a][0] * gam; Sacc[a][1] = Sacc[a][1] * gam; }
;                                 {
;                                     bf16x8 vq[2][R2_NCT];
; #pragma unroll
;                                     for (int dt = 0; dt < R2_NCT; ++dt) vq[0][dt] = *(const bf16x8*)(VT + (dt * 16 + r16) * 136 + g4 * 8);
; #pragma unroll
;                                     for (int q = 0; q < 4; ++q) {
;                                         if (q + 1 < 4) {
; #pragma unroll
;                                             for (int dt = 0; dt < R2_NCT; ++dt) vq[(q + 1) & 1][dt] = *(const bf16x8*)(VT + (dt * 16 + r16) * 136 + (q + 1) * 32 + g4 * 8); }
;                                         __builtin_amdgcn_sched_barrier(0);
; #pragma unroll
;                                         for (int dt = 0; dt < R2_NCT; ++dt) { Sacc[dt][0] = MFMA16(vq[q & 1][dt], kfr[2 * q], Sacc[dt][0]); Sacc[dt][1] = MFMA16(vq[q & 1][dt], kfr[2 * q + 1], Sacc[dt][1]); }
	v_mfma_f32_16x16x32_bf16 v[28:31], v[28:31], v[12:15], v[32:35]
	s_waitcnt lgkmcnt(4)
	v_mfma_f32_16x16x32_bf16 v[12:15], v[60:63], v[12:15], v[16:19]
	s_nop 2
	ds_read_b128 v[16:19], v115 offset:33984
	ds_read_b128 v[32:35], v136 offset:33984
	s_waitcnt lgkmcnt(5)
	v_mfma_f32_16x16x32_bf16 v[24:27], v[24:27], v[8:11], v[28:31]
	s_waitcnt lgkmcnt(4)
	v_mfma_f32_16x16x32_bf16 v[8:11], v[40:43], v[8:11], v[12:15]
	s_waitcnt lgkmcnt(3)
	v_mfma_f32_16x16x32_bf16 v[12:15], v[20:23], v[4:7], v[24:27]
	s_waitcnt lgkmcnt(2)
	v_mfma_f32_16x16x32_bf16 v[4:7], v[36:39], v[4:7], v[8:11]
	s_waitcnt lgkmcnt(1)
	v_mfma_f32_16x16x32_bf16 v[132:135], v[16:19], v[0:3], v[12:15]
	s_waitcnt lgkmcnt(0)
	v_mfma_f32_16x16x32_bf16 v[136:139], v[32:35], v[0:3], v[4:7]
	v_lshl_add_u64 v[0:1], s[0:1], 0, v[172:173]
	v_mad_u64_u32 v[2:3], s[10:11], v0, s69, v[180:181]
	v_mov_b32_e32 v0, v3
	v_mad_u64_u32 v[0:1], s[10:11], v1, s69, v[0:1]
	v_mov_b32_e32 v3, v0
	global_load_dwordx4 v[60:63], v[2:3], off
	global_load_dwordx4 v[12:15], v[2:3], off offset:2048
	v_lshl_add_u64 v[176:177], v[2:3], 0, v[170:171]
	global_load_dwordx4 v[40:43], v[176:177], off
	v_mov_b32_e32 v8, 0
	v_mov_b32_e32 v9, 0
	v_mov_b32_e32 v10, 0
	v_mov_b32_e32 v11, 0
	v_cmp_le_u32_e32 vcc, 0x80, v199
	s_mov_b64 exec, vcc
	global_load_dwordx4 v[8:11], v[176:177], off offset:2048
	s_mov_b64 exec, -1
	v_lshl_add_u64 v[176:177], v[176:177], 0, v[170:171]
	global_load_dwordx4 v[36:39], v[176:177], off
	v_mov_b32_e32 v4, 0
	v_mov_b32_e32 v5, 0
	v_mov_b32_e32 v6, 0
	v_mov_b32_e32 v7, 0
	v_cmp_le_u32_e32 vcc, 0x100, v199
	s_mov_b64 exec, vcc
	global_load_dwordx4 v[4:7], v[176:177], off offset:2048
	s_mov_b64 exec, -1
	v_lshl_add_u64 v[176:177], v[176:177], 0, v[170:171]
	global_load_dwordx4 v[32:35], v[176:177], off
	v_mov_b32_e32 v0, 0
	v_mov_b32_e32 v1, 0
	v_mov_b32_e32 v2, 0
	v_mov_b32_e32 v3, 0
	v_cmp_le_u32_e32 vcc, 0x180, v199
	s_mov_b64 exec, vcc
	global_load_dwordx4 v[0:3], v[176:177], off offset:2048
	s_mov_b64 exec, -1
	v_lshl_add_u64 v[176:177], v[176:177], 0, v[170:171]
	global_load_dwordx4 v[28:31], v[176:177], off
	v_lshl_add_u64 v[176:177], v[176:177], 0, v[170:171]
	global_load_dwordx4 v[24:27], v[176:177], off
	v_lshl_add_u64 v[176:177], v[176:177], 0, v[170:171]
	global_load_dwordx4 v[20:23], v[176:177], off
	v_lshl_add_u64 v[176:177], v[176:177], 0, v[170:171]
	global_load_dwordx4 v[16:19], v[176:177], off
	v_lshl_add_u64 v[84:85], s[0:1], 0, v[104:105]
	v_mov_b64_e32 v[86:87], s[52:53]
	v_mad_u64_u32 v[86:87], s[0:1], v84, s69, v[86:87]
	v_mov_b32_e32 v84, v87
	v_mad_u64_u32 v[84:85], s[0:1], v85, s69, v[84:85]
	v_mov_b32_e32 v87, v84
	v_lshl_add_u64 v[84:85], v[86:87], 0, s[94:95]
	v_lshl_add_u64 v[84:85], s[2:3], 1, v[84:85]
	v_lshl_add_u64 v[84:85], v[84:85], 0, v[112:113]
	v_add_co_u32_e64 v84, s[0:1], s64, v84
	v_cvt_pk_bf16_f32 v132, v132, v133
	s_nop 0
	v_addc_co_u32_e64 v85, s[0:1], 0, v85, s[0:1]
	global_load_dwordx4 v[84:87], v[84:85], off
	v_cvt_pk_bf16_f32 v133, v134, v135
	global_store_dwordx2 v[122:123], v[132:133], off offset:-32
	v_cvt_pk_bf16_f32 v132, v136, v137
	v_cvt_pk_bf16_f32 v133, v138, v139
	v_mov_b32_e32 v115, v114
	global_store_dwordx2 v[122:123], v[132:133], off
	v_pk_mul_f32 v[98:99], v[114:115], v[98:99]
	v_pk_mul_f32 v[94:95], v[114:115], v[94:95]
	v_pk_mul_f32 v[90:91], v[114:115], v[90:91]
	v_pk_mul_f32 v[82:83], v[114:115], v[82:83]
	v_add_u32_e32 v115, v131, v126
	ds_read_b128 v[132:135], v115 offset:33792
	ds_read_b128 v[136:139], v115 offset:38144
	ds_read_b128 v[140:143], v115 offset:33856
	ds_read_b128 v[144:147], v115 offset:38208
	v_pk_mul_f32 v[96:97], v[120:121], v[96:97]
	v_pk_mul_f32 v[92:93], v[120:121], v[92:93]
	v_pk_mul_f32 v[88:89], v[120:121], v[88:89]
	v_pk_mul_f32 v[80:81], v[120:121], v[80:81]
	s_waitcnt lgkmcnt(3)
	v_mfma_f32_16x16x32_bf16 v[96:99], v[132:135], v[52:55], v[96:99]
	s_nop 0
	v_mfma_f32_16x16x32_bf16 v[92:95], v[132:135], v[76:79], v[92:95]
	s_waitcnt lgkmcnt(2)
	v_mfma_f32_16x16x32_bf16 v[52:55], v[136:139], v[52:55], v[88:91]
	v_mfma_f32_16x16x32_bf16 v[76:79], v[136:139], v[76:79], v[80:83]
	s_nop 2
	ds_read_b128 v[80:83], v115 offset:33920
	ds_read_b128 v[88:91], v115 offset:38272
	s_waitcnt lgkmcnt(3)
; __device__ __forceinline__ unsigned f2bf(float f) { return pk2(f, 0.f) & 0xffffu; }
; #define MFMA16(a, b, c) __builtin_amdgcn_mfma_f32_16x16x32_bf16((a), (b), (c), 0, 0, 0)
; #define R2_LOAD_K(nn) do { const bf16* kdt_ = KDT + ((size_t)bh * 64 + (nn)) * 32768; \
;     _Pragma("unroll") for (int q = 0; q < 4; ++q) { kfr[2 * q] = *(const bf16x8*)(kdt_ + ((2 * wave) * 16 + r16) * 128 + q * 32 + g4 * 8); kfr[2 * q + 1] = *(const bf16x8*)(kdt_ + ((2 * wave + 1) * 16 + r16) * 128 + q * 32 + g4 * 8); } } while (0)
; __global__ void __launch_bounds__(512, 2) fwd_megakernel(Params kp_) {
;     ...
;                                 {
;                                     bf16x8 vq[2][R2_NCT];
; #pragma unroll
;                                     for (int dt = 0; dt < R2_NCT; ++dt) vq[0][dt] = *(const bf16x8*)(VT + (dt * 16 + r16) * 136 + g4 * 8);
; #pragma unroll
;                                     for (int q = 0; q < 4; ++q) {
;                                         if (q + 1 < 4) {
; #pragma unroll
;                                             for (int dt = 0; dt < R2_NCT; ++dt) vq[(q + 1) & 1][dt] = *(const bf16x8*)(VT + (dt * 16 + r16) * 136 + (q + 1) * 32 + g4 * 8); }
;                                         __builtin_amdgcn_sched_barrier(0);
; #pragma unroll
;                                         for (int dt = 0; dt < R2_NCT; ++dt) { Sacc[dt][0] = MFMA16(vq[q & 1][dt], kfr[2 * q], Sacc[dt][0]); Sacc[dt][1] = MFMA16(vq[q & 1][dt], kfr[2 * q + 1], Sacc[dt][1]); }
;                                         __builtin_amdgcn_sched_barrier(0);
;                                     }
;                                 }
;                                 R2_LOAD_K(n < 63 ? n + 1 : n);
; #pragma unroll
;                                 for (int dt = 0; dt < R2_NCT; ++dt)
; #pragma unroll
;                                     for (int kt = 0; kt < 2; ++kt)
; #pragma unroll
;                                         for (int j = 0; j < 4; ++j) STn[(dt * 16 + g4 * 4 + j) * 264 + (2 * wave + kt) * 16 + r16] = (bf16)f2bf(Sacc[dt][kt][j]);
	v_mfma_f32_16x16x32_bf16 v[96:99], v[140:143], v[68:71], v[96:99]
	s_nop 0
	v_mfma_f32_16x16x32_bf16 v[92:95], v[140:143], v[72:75], v[92:95]
	s_waitcnt lgkmcnt(2)
	v_mfma_f32_16x16x32_bf16 v[52:55], v[144:147], v[68:71], v[52:55]
	v_mfma_f32_16x16x32_bf16 v[68:71], v[144:147], v[72:75], v[76:79]
	ds_read_b128 v[72:75], v115 offset:33984
	s_nop 1
	ds_read_b128 v[76:79], v115 offset:38336
	s_waitcnt lgkmcnt(3)
	v_mfma_f32_16x16x32_bf16 v[96:99], v[80:83], v[48:51], v[96:99]
	s_nop 0
	v_mfma_f32_16x16x32_bf16 v[80:83], v[80:83], v[64:67], v[92:95]
	s_waitcnt lgkmcnt(2)
	v_mfma_f32_16x16x32_bf16 v[48:51], v[88:91], v[48:51], v[52:55]
	v_mfma_f32_16x16x32_bf16 v[52:55], v[88:91], v[64:67], v[68:71]
	s_waitcnt lgkmcnt(1)
	v_mfma_f32_16x16x32_bf16 v[96:99], v[72:75], v[44:47], v[96:99]
	s_nop 0
	v_mfma_f32_16x16x32_bf16 v[92:95], v[72:75], v[56:59], v[80:83]
	s_waitcnt lgkmcnt(0)
	v_mfma_f32_16x16x32_bf16 v[88:91], v[76:79], v[44:47], v[48:51]
	v_mfma_f32_16x16x32_bf16 v[80:83], v[76:79], v[56:59], v[52:55]
	s_mov_b32 s7, s95
	s_waitcnt vmcnt(15)
	v_mov_b32_e32 v68, v204
	v_mov_b32_e32 v69, v205
	v_mov_b32_e32 v70, v206
	v_mov_b32_e32 v71, v207
	v_mov_b32_e32 v72, v208
	v_mov_b32_e32 v73, v209
	v_mov_b32_e32 v74, v210
	v_mov_b32_e32 v75, v211
	v_mov_b32_e32 v64, v212
	v_mov_b32_e32 v65, v213
	v_mov_b32_e32 v66, v214
	v_mov_b32_e32 v67, v215
	v_mov_b32_e32 v76, v224
	v_mov_b32_e32 v77, v225
	v_mov_b32_e32 v78, v226
	v_mov_b32_e32 v79, v227
	v_mov_b32_e32 v44, v220
	v_mov_b32_e32 v45, v221
	v_mov_b32_e32 v46, v222
	v_mov_b32_e32 v47, v223
	v_mov_b32_e32 v56, v228
	v_mov_b32_e32 v57, v229
	v_mov_b32_e32 v58, v230
	v_mov_b32_e32 v59, v231
	v_mov_b32_e32 v48, v216
	v_mov_b32_e32 v49, v217
	v_mov_b32_e32 v50, v218
	v_mov_b32_e32 v51, v219
	v_mov_b32_e32 v52, v200
	v_mov_b32_e32 v53, v201
	v_mov_b32_e32 v54, v202
	v_mov_b32_e32 v55, v203
	s_mov_b32 s101, s95
	v_lshl_add_u64 v[232:233], s[100:101], 1, v[116:117]
	s_nop 0
	v_add_co_u32_e64 v236, s[0:1], s64, v232
	v_lshl_add_u64 v[234:235], v[232:233], 0, s[90:91]
	s_nop 0
	v_addc_co_u32_e64 v237, s[0:1], 0, v233, s[0:1]
	global_load_dwordx4 v[200:203], v[232:233], off
	global_load_dwordx4 v[204:207], v[232:233], off offset:1024
	global_load_dwordx4 v[208:211], v[234:235], off offset:1024
	global_load_dwordx4 v[212:215], v[234:235], off offset:2048
	global_load_dwordx4 v[216:219], v[232:233], off offset:2048
	global_load_dwordx4 v[220:223], v[232:233], off offset:3072
	global_load_dwordx4 v[224:227], v[236:237], off
	global_load_dwordx4 v[228:231], v[234:235], off offset:3072
	s_cselect_b32 s0, 0x4200, 0
	v_cvt_pk_bf16_f32 v115, v96, s0
	v_add_u32_e32 v131, s0, v128
	ds_write_b16 v131, v115
	v_cvt_pk_bf16_f32 v115, v97, s0
	ds_write_b16 v131, v115 offset:528
	v_cvt_pk_bf16_f32 v115, v98, s0
	ds_write_b16 v131, v115 offset:1056
	v_cvt_pk_bf16_f32 v115, v99, s0
	ds_write_b16 v131, v115 offset:1584
	v_cvt_pk_bf16_f32 v115, v92, s0
	ds_write_b16 v131, v115 offset:32
	v_cvt_pk_bf16_f32 v115, v93, s0
	ds_write_b16 v131, v115 offset:560
	v_cvt_pk_bf16_f32 v115, v94, s0
	ds_write_b16 v131, v115 offset:1088
	v_cvt_pk_bf16_f32 v115, v95, s0
	ds_write_b16 v131, v115 offset:1616
	v_cvt_pk_bf16_f32 v115, v88, s0
	ds_write_b16 v131, v115 offset:8448
	v_cvt_pk_bf16_f32 v115, v89, s0
	ds_write_b16 v131, v115 offset:8976
	v_cvt_pk_bf16_f32 v115, v90, s0
	ds_write_b16 v131, v115 offset:9504
	v_cvt_pk_bf16_f32 v115, v91, s0
	ds_write_b16 v131, v115 offset:10032
	v_cvt_pk_bf16_f32 v115, v80, s0
	ds_write_b16 v131, v115 offset:8480
	v_cvt_pk_bf16_f32 v115, v81, s0
	ds_write_b16 v131, v115 offset:9008
	v_cvt_pk_bf16_f32 v115, v82, s0
	ds_write_b16 v131, v115 offset:9536
	v_cvt_pk_bf16_f32 v115, v83, s0
	s_add_i32 s8, s8, 0x8000
	s_mov_b64 s[0:1], 0x184000
	v_lshl_add_u64 v[122:123], v[122:123], 0, s[0:1]
	s_cmp_eq_u32 s9, 64
	s_mov_b64 s[6:7], s[4:5]
	s_mov_b32 s0, s9
	ds_write_b16 v131, v115 offset:10064
	s_cbranch_scc0 .LBB0_558
	v_readlane_b32 s0, v254, 14
	s_add_i32 s17, s17, s88
	s_add_i32 s16, s16, s0
	s_cmpk_gt_i32 s17, 0xff
	s_cbranch_scc0 .LBB0_554
